# v21: v15 + cooperative grid sync removed + attention ping-pong (waves 4-7 one barrier behind) + hand-scheduled softmax/PV block (permlane-swap row max, in-place P, prefetched V fragments)
# baseline (speedup 1.0000x reference)
; __device__ __forceinline__ void attn_phase(LAS unsigned char* lds, const bf16_t* Q, const bf16_t* KN, const bf16_t* P, const bf16_t* VT, bf16_t* CAT, int bid, int G, const int tid) {
;     ...
;         const int rnd = u >> 8, c = u & 255, bh = c >> 1, half = c & 1;
;         const int qb = half ? (rnd == 0 ? 5 : rnd == 1 ? 2 : rnd == 2 ? 4 : 3) : (rnd == 0 ? 7 : rnd == 1 ? 0 : rnd == 2 ? 6 : 1);
;         const int b = bh >> 3, hh = bh & 7, nt = 4 * (qb + 1);
;         const size_t tok0 = (size_t)b * SEQ;
;         const int qlo = qb * 256 + 32 * w;
;         bf16x8 qf[2][6];
; #pragma unroll
;         for (int qi = 0; qi < 2; ++qi)
; #pragma unroll
;             for (int ch = 0; ch < 6; ++ch) qf[qi][ch] = *(const bf16x8*)(Q + (tok0 + qlo + 16 * qi + fr) * QW + hh * 192 + ch * 32 + fq * 8);
;         f32x4 o[8][2];
; #pragma unroll
;         for (int d = 0; d < 8; ++d) { o[d][0] = (f32x4){0.f, 0.f, 0.f, 0.f}; o[d][1] = (f32x4){0.f, 0.f, 0.f, 0.f}; }
;         float mrow[2] = {-INFINITY, -INFINITY}, lrow[2] = {0.f, 0.f};
;         const int kkey0 = tid >> 4, kc16 = tid & 15;
;         const int pkey = tid >> 3, pc8 = tid & 7;
;         const int vd0 = tid >> 3, vc8 = tid & 7;
;         const bf16_t* gk = KN + (tok0 + kkey0) * 1024 + hh * 128 + kc16 * 8;
;         const bf16_t* gp = P + (tok0 + pkey) * P_LD + OFF_KPE + pc8 * 8;
;         const bf16_t* gv = VT + (size_t)(hh * 128 + vd0) * M + tok0 + vc8 * 8;
;         const int lk = (kkey0 * KS + kc16 * 8) * 2, lp = (pkey * KS + 128 + pc8 * 8) * 2, lv = KBYTES + (vd0 * VS + vc8 * 8) * 2;
;         u32x4 rk0, rk1, rp, rv0, rv1;
;         rk0 = *(const u32x4*)(gk); rk1 = *(const u32x4*)(gk + 32 * 1024); rp = *(const u32x4*)(gp);
;         rv0 = *(const u32x4*)(gv); rv1 = *(const u32x4*)(gv + (size_t)64 * M);
;         for (int kt = 0; kt < nt; ++kt) {
;             LAS unsigned char* buf = lds + (kt & 1) * BUFB;
;             *(LAS u32x4*)(buf + lk) = rk0; *(LAS u32x4*)(buf + lk + 32 * KS * 2) = rk1; *(LAS u32x4*)(buf + lp) = rp;
;             *(LAS u32x4*)(buf + lv) = rv0; *(LAS u32x4*)(buf + lv + 64 * VS * 2) = rv1;
;             __syncthreads();
;             if (kt + 1 < nt) {
;                 const size_t ko = (size_t)(kt + 1) * 64;
;                 rk0 = *(const u32x4*)(gk + ko * 1024); rk1 = *(const u32x4*)(gk + (ko + 32) * 1024); rp = *(const u32x4*)(gp + ko * P_LD);
.LBB0_143:
	s_bfe_u32 s4, s13, 0x4000b
	s_bfe_u32 s30, s17, 0x30001
	v_mad_u64_u32 v[164:165], s[4:5], s4, v232, v[194:195]
	s_lshl_b32 s20, s30, 7
	s_lshl_b32 s4, s13, 11
	v_add_u32_e32 v0, s20, v188
	s_and_b32 s5, s4, 0x3c00000
	s_lshl_b32 s4, s30, 8
	v_ashrrev_i32_e32 v1, 31, v0
	s_or_b32 s26, s4, s5
	v_lshlrev_b64 v[0:1], 16, v[0:1]
	s_lshl_b32 s5, s13, 1
	v_or_b32_e32 v2, v192, v0
	s_and_b32 s5, s5, 0xf000
	s_lshl_b32 s34, s38, 8
	v_or_b32_e32 v168, s5, v2
	s_lshl_b32 s5, s17, 7
	s_add_i32 s21, s34, s3
	v_lshl_add_u64 v[166:167], s[26:27], 0, v[196:197]
	s_and_b32 s26, s5, 0x7800
	s_ashr_i32 s5, s21, 31
	s_add_u32 s31, s21, s26
	v_or_b32_e32 v200, s31, v178
	s_mulk_i32 s30, 0x180
	s_mov_b32 s31, s27
	v_lshl_add_u64 v[2:3], v[184:185], 0, s[30:31]
	s_addc_u32 s5, s5, 0
	v_mad_u64_u32 v[2:3], s[30:31], v200, s9, v[2:3]
	v_mad_i32_i24 v3, s5, v233, v3
	s_mov_b64 s[30:31], 0xc000
	flat_load_dwordx4 v[104:107], v[2:3]
	flat_load_dwordx4 v[92:95], v[2:3] offset:64
	flat_load_dwordx4 v[88:91], v[2:3] offset:128
	flat_load_dwordx4 v[76:79], v[2:3] offset:192
	flat_load_dwordx4 v[72:75], v[2:3] offset:256
	flat_load_dwordx4 v[64:67], v[2:3] offset:320
	v_lshl_add_u64 v[4:5], v[2:3], 0, s[30:31]
	v_add_co_u32_e32 v2, vcc, s73, v2
	v_readlane_b32 s38, v255, 4
	s_nop 0
	v_addc_co_u32_e32 v3, vcc, 0, v3, vcc
	flat_load_dwordx4 v[108:111], v[2:3]
	flat_load_dwordx4 v[100:103], v[4:5] offset:64
	flat_load_dwordx4 v[96:99], v[4:5] offset:128
	flat_load_dwordx4 v[84:87], v[4:5] offset:192
	flat_load_dwordx4 v[80:83], v[4:5] offset:256
	flat_load_dwordx4 v[68:71], v[4:5] offset:320
	v_lshl_add_u64 v[2:3], s[26:27], 0, v[186:187]
	v_lshlrev_b64 v[2:3], 11, v[2:3]
	v_readlane_b32 s39, v255, 5
	v_mov_b32_e32 v201, s5
	s_mov_b32 s5, s27
	v_lshl_add_u64 v[2:3], s[38:39], 0, v[2:3]
	v_lshl_add_u64 v[2:3], v[2:3], 0, s[4:5]
	v_lshl_add_u64 v[2:3], v[2:3], 0, v[176:177]
	v_add_u32_e32 v6, s26, v188
	v_mov_b64_e32 v[4:5], s[10:11]
	v_mad_i64_i32 v[4:5], s[4:5], v6, s48, v[4:5]
	v_mov_b32_e32 v199, v177
	flat_load_dwordx4 v[112:115], v[2:3]
	v_add_co_u32_e32 v2, vcc, 0x10000, v2
	v_mov_b32_e32 v169, v1
	v_lshl_add_u64 v[4:5], v[4:5], 0, v[198:199]
	v_lshl_add_u64 v[0:1], s[54:55], 0, v[0:1]
	s_lshl_b32 s26, s26, 1
	v_addc_co_u32_e32 v3, vcc, 0, v3, vcc
	v_lshl_add_u64 v[0:1], v[0:1], 0, s[26:27]
	flat_load_dwordx4 v[116:119], v[2:3]
	v_add_co_u32_e32 v2, vcc, 0x1000, v4
	v_lshl_add_u64 v[0:1], v[0:1], 0, v[198:199]
	s_nop 0
	v_addc_co_u32_e32 v3, vcc, 0, v5, vcc
	flat_load_dwordx4 v[120:123], v[2:3] offset:2176
	flat_load_dwordx4 v[124:127], v[0:1]
	v_add_co_u32_e32 v0, vcc, 0x400000, v0
	v_mov_b32_e32 v28, v177
	s_nop 0
	v_addc_co_u32_e32 v1, vcc, 0, v1, vcc
	flat_load_dwordx4 v[128:131], v[0:1]
	v_mov_b32_e32 v29, v177
	v_mov_b32_e32 v30, v177
	v_mov_b32_e32 v31, v177
	v_or_b32_e32 v244, s21, v178
	v_mov_b64_e32 v[62:63], v[30:31]
	v_mov_b64_e32 v[24:25], v[28:29]
	v_mov_b64_e32 v[58:59], v[30:31]
	v_mov_b64_e32 v[20:21], v[28:29]
	v_mov_b64_e32 v[50:51], v[30:31]
	v_mov_b64_e32 v[16:17], v[28:29]
	v_mov_b64_e32 v[54:55], v[30:31]
	v_mov_b64_e32 v[12:13], v[28:29]
	v_mov_b64_e32 v[46:47], v[30:31]
	v_mov_b64_e32 v[8:9], v[28:29]
	v_mov_b64_e32 v[42:43], v[30:31]
	v_mov_b64_e32 v[4:5], v[28:29]
	v_mov_b64_e32 v[38:39], v[30:31]
	v_mov_b64_e32 v[0:1], v[28:29]
	v_mov_b64_e32 v[34:35], v[30:31]
	s_mov_b32 s30, 0
	s_or_b32 s26, s21, 31
	v_or_b32_e32 v199, 16, v244
	s_or_b32 s31, s34, 0xc0
	v_mov_b32_e32 v202, v177
	v_mov_b32_e32 v203, v177
	v_mov_b32_e32 v206, 0xff800000
	v_mov_b64_e32 v[60:61], v[28:29]
	v_mov_b64_e32 v[26:27], v[30:31]
	v_mov_b64_e32 v[56:57], v[28:29]
	v_mov_b64_e32 v[22:23], v[30:31]
	v_mov_b64_e32 v[48:49], v[28:29]
	v_mov_b64_e32 v[18:19], v[30:31]
	v_mov_b64_e32 v[52:53], v[28:29]
	v_mov_b64_e32 v[14:15], v[30:31]
	v_mov_b64_e32 v[44:45], v[28:29]
	v_mov_b64_e32 v[10:11], v[30:31]
	v_mov_b64_e32 v[40:41], v[28:29]
	v_mov_b64_e32 v[6:7], v[30:31]
	v_mov_b64_e32 v[36:37], v[28:29]
	v_mov_b64_e32 v[2:3], v[30:31]
	v_mov_b64_e32 v[32:33], v[28:29]
	v_mov_b32_e32 v207, 0xff800000
	s_mov_b32 s34, 0
	v_readfirstlane_b32 s80, v179
	s_lshr_b32 s80, s80, 8
	s_mov_b32 s4, 0
	v_add_u32_e32 v228, s4, v183
	s_waitcnt vmcnt(0) lgkmcnt(0)
	ds_write_b128 v228, v[112:115]
	ds_write_b128 v228, v[116:119] offset:12800
	v_add_u32_e32 v229, s4, v240
	ds_write_b128 v229, v[120:123]
	v_add_u32_e32 v228, s4, v241
	ds_write_b128 v228, v[124:127] offset:25600
	ds_write_b128 v228, v[128:131] offset:34816
	v_lshl_add_u64 v[112:113], s[24:25], 0, v[166:167]
	s_mov_b32 s4, 0x1c220000
	v_add_co_u32_e32 v114, vcc, s4, v112
	s_mov_b32 s4, 0x1c230000
	s_nop 0
	v_addc_co_u32_e32 v115, vcc, 0, v113, vcc
	v_add_co_u32_e32 v116, vcc, s4, v112
	v_lshl_add_u64 v[128:129], s[24:25], 0, v[168:169]
	s_nop 0
	v_addc_co_u32_e32 v117, vcc, 0, v113, vcc
	v_add_co_u32_e32 v124, vcc, 0x20200000, v128
	v_lshl_add_u64 v[120:121], s[24:25], 0, v[164:165]
	s_nop 0
	v_addc_co_u32_e32 v125, vcc, 0, v129, vcc
	v_add_co_u32_e32 v128, vcc, 0x20600000, v128
	s_waitcnt lgkmcnt(0)
	s_nop 0
	v_addc_co_u32_e32 v129, vcc, 0, v129, vcc
	s_nop 0
	global_load_dwordx4 v[112:115], v[114:115], off
	s_nop 0
	global_load_dwordx4 v[116:119], v[116:117], off
	s_nop 0
	global_load_dwordx4 v[120:123], v[120:121], off
	s_nop 0
	global_load_dwordx4 v[124:127], v[124:125], off offset:128
	global_load_dwordx4 v[128:131], v[128:129], off offset:128
	s_mov_b64 s[4:5], 0x68000
	v_lshl_add_u64 v[164:165], v[164:165], 0, s[4:5]
	s_mov_b64 s[4:5], 0x20000
	v_lshl_add_u64 v[166:167], v[166:167], 0, s[4:5]
	v_lshl_add_u64 v[168:169], v[168:169], 0, s[22:23]
	s_cmp_eq_u32 s80, 0
	s_cbranch_scc1 .Lat_pro_done
	s_waitcnt lgkmcnt(0)
	s_barrier
; #define LAS __attribute__((address_space(3)))
; __device__ __forceinline__ void attn_phase(LAS unsigned char* lds, const bf16_t* Q, const bf16_t* KN, const bf16_t* P, const bf16_t* VT, bf16_t* CAT, int bid, int G, const int tid) {
;     ...
;                 for (int qi = 0; qi < 2; ++qi) {
;                     float mx = -INFINITY;
; #pragma unroll
;                     for (int kb = 0; kb < 4; ++kb) mx = fmaxf(mx, fmaxf(fmaxf(s[kb][qi][0], s[kb][qi][1]), fmaxf(s[kb][qi][2], s[kb][qi][3])));
;                     mx = fmaxf(mx, __shfl_xor(mx, 16)); mx = fmaxf(mx, __shfl_xor(mx, 32));
;                     const float mnew = fmaxf(mrow[qi], mx);
;                     const float alpha = __builtin_amdgcn_exp2f(mrow[qi] - mnew);
;                     mrow[qi] = mnew;
;                     float ps = 0.f;
; #pragma unroll
;                     for (int kb = 0; kb < 4; ++kb)
; #pragma unroll
;                         for (int j = 0; j < 4; ++j) { const float e = __builtin_amdgcn_exp2f(s[kb][qi][j] - mnew); s[kb][qi][j] = e; ps += e; }
;                     lrow[qi] = lrow[qi] * alpha + ps;
; #pragma unroll
;                     for (int d = 0; d < 8; ++d) o[d][qi] = o[d][qi] * alpha;
; #pragma unroll
;                     for (int cc = 0; cc < 2; ++cc) {
;                         u32x4 t; t.x = cvt_pk_bf16(s[2 * cc][qi][0], s[2 * cc][qi][1]); t.y = cvt_pk_bf16(s[2 * cc][qi][2], s[2 * cc][qi][3]);
;                         t.z = cvt_pk_bf16(s[2 * cc + 1][qi][0], s[2 * cc + 1][qi][1]); t.w = cvt_pk_bf16(s[2 * cc + 1][qi][2], s[2 * cc + 1][qi][3]);
;                         pf[qi][cc] = __builtin_bit_cast(bf16x8, t);
;                     }
;                 }
; #pragma unroll
;                 for (int cc = 0; cc < 2; ++cc)
; #pragma unroll
;                     for (int d = 0; d < 8; ++d) {
;                         const LAS unsigned char* vp = buf + KBYTES + ((d * 16 + fr) * VS + 32 * cc + 4 * fq) * 2;
;                         const u32x2 v0 = *(const LAS u32x2*)vp, v1 = *(const LAS u32x2*)(vp + 32);
;                         const u32x4 vv = {v0.x, v0.y, v1.x, v1.y};
;                         const bf16x8 vf = __builtin_bit_cast(bf16x8, vv);
;                         o[d][0] = __builtin_amdgcn_mfma_f32_16x16x32_bf16(vf, pf[0][cc], o[d][0], 0, 0, 0);
;                         o[d][1] = __builtin_amdgcn_mfma_f32_16x16x32_bf16(vf, pf[1][cc], o[d][1], 0, 0, 0);
.Lat_pro_done:
	s_branch .LBB0_146
.LBB0_144:
	v_add3_u32 v174, s35, v180, v243
	v_add_u32_e32 v175, 0x6400, v174
	ds_read2_b64 v[208:211], v175 offset1:4
	v_add_u32_e32 v172, 0x6d00, v174
	ds_read2_b64 v[212:215], v172 offset1:4
	v_add_u32_e32 v173, 0x7600, v174
	ds_read2_b64 v[216:219], v173 offset1:4
	v_add_u32_e32 v175, 0x7f00, v174
	ds_read2_b64 v[220:223], v175 offset1:4
	v_add_u32_e32 v172, 0x8800, v174
	ds_read2_b64 v[224:227], v172 offset1:4
	v_max3_f32 v170, v132, v133, v134
	v_max3_f32 v204, v148, v149, v150
	v_max3_f32 v171, v135, v136, v137
	v_max3_f32 v205, v151, v156, v157
	v_max3_f32 v170, v170, v138, v139
	v_max3_f32 v204, v204, v158, v159
	v_max3_f32 v171, v171, v140, v141
	v_max3_f32 v205, v205, v152, v153
	v_max3_f32 v170, v170, v142, v143
	v_max3_f32 v204, v204, v154, v155
	v_max3_f32 v171, v171, v144, v145
	v_max3_f32 v205, v205, v160, v161
	v_max3_f32 v170, v170, v146, v147
	v_max3_f32 v204, v204, v162, v163
	v_max_f32_e32 v170, v170, v171
	v_max_f32_e32 v204, v204, v205
	v_mov_b32_e32 v171, v170
	v_mov_b32_e32 v205, v204
	s_nop 1
	v_permlane16_swap_b32 v170, v171
	v_permlane16_swap_b32 v204, v205
	v_max_f32_e32 v170, v170, v171
	v_max_f32_e32 v204, v204, v205
	v_mov_b32_e32 v171, v170
	v_mov_b32_e32 v205, v204
	s_nop 1
	v_permlane32_swap_b32 v170, v171
	v_permlane32_swap_b32 v204, v205
	v_max3_f32 v245, v207, v170, v171
	v_max3_f32 v246, v206, v204, v205
	v_sub_f32_e32 v171, v207, v245
	v_sub_f32_e32 v205, v206, v246
	v_exp_f32_e32 v230, v171
	v_exp_f32_e32 v252, v205
	v_pk_add_f32 v[132:133], v[132:133], v[244:245] op_sel:[0,1] op_sel_hi:[1,1] neg_lo:[0,1] neg_hi:[0,1]
	v_pk_add_f32 v[148:149], v[148:149], v[246:247] op_sel_hi:[1,0] neg_lo:[0,1] neg_hi:[0,1]
	v_pk_add_f32 v[134:135], v[134:135], v[244:245] op_sel:[0,1] op_sel_hi:[1,1] neg_lo:[0,1] neg_hi:[0,1]
	v_pk_add_f32 v[150:151], v[150:151], v[246:247] op_sel_hi:[1,0] neg_lo:[0,1] neg_hi:[0,1]
	v_pk_add_f32 v[136:137], v[136:137], v[244:245] op_sel:[0,1] op_sel_hi:[1,1] neg_lo:[0,1] neg_hi:[0,1]
	v_pk_add_f32 v[156:157], v[156:157], v[246:247] op_sel_hi:[1,0] neg_lo:[0,1] neg_hi:[0,1]
	v_pk_add_f32 v[138:139], v[138:139], v[244:245] op_sel:[0,1] op_sel_hi:[1,1] neg_lo:[0,1] neg_hi:[0,1]
	v_pk_add_f32 v[158:159], v[158:159], v[246:247] op_sel_hi:[1,0] neg_lo:[0,1] neg_hi:[0,1]
	v_exp_f32_e32 v132, v132
	v_exp_f32_e32 v148, v148
	v_exp_f32_e32 v133, v133
	v_exp_f32_e32 v149, v149
	v_exp_f32_e32 v134, v134
	v_exp_f32_e32 v150, v150
	v_exp_f32_e32 v135, v135
	v_exp_f32_e32 v151, v151
	v_exp_f32_e32 v136, v136
	v_exp_f32_e32 v156, v156
	v_exp_f32_e32 v137, v137
	v_exp_f32_e32 v157, v157
	v_exp_f32_e32 v138, v138
	v_exp_f32_e32 v158, v158
	v_exp_f32_e32 v139, v139
	v_exp_f32_e32 v159, v159
	v_pk_mul_f32 v[32:33], v[32:33], v[230:231] op_sel_hi:[1,0]
	v_pk_mul_f32 v[34:35], v[34:35], v[230:231] op_sel_hi:[1,0]
	v_pk_mul_f32 v[0:1], v[0:1], v[252:253] op_sel_hi:[1,0]
	v_pk_mul_f32 v[2:3], v[2:3], v[252:253] op_sel_hi:[1,0]
	v_pk_add_f32 v[228:229], v[132:133], v[134:135]
	v_pk_add_f32 v[170:171], v[148:149], v[150:151]
	v_pk_add_f32 v[228:229], v[228:229], v[136:137]
	v_pk_add_f32 v[170:171], v[170:171], v[156:157]
	v_pk_add_f32 v[228:229], v[228:229], v[138:139]
	v_pk_add_f32 v[170:171], v[170:171], v[158:159]
	v_cvt_pk_bf16_f32 v132, v132, v133
	v_cvt_pk_bf16_f32 v133, v134, v135
	v_cvt_pk_bf16_f32 v134, v136, v137
	v_cvt_pk_bf16_f32 v135, v138, v139
	v_cvt_pk_bf16_f32 v148, v148, v149
	v_cvt_pk_bf16_f32 v149, v150, v151
	v_cvt_pk_bf16_f32 v150, v156, v157
	v_cvt_pk_bf16_f32 v151, v158, v159
	v_add_u32_e32 v173, 0x9100, v174
	ds_read2_b64 v[136:139], v173 offset1:4
	v_add_u32_e32 v175, 0x9a00, v174
	ds_read2_b64 v[156:159], v175 offset1:4
	v_pk_mul_f32 v[36:37], v[36:37], v[230:231] op_sel_hi:[1,0]
	v_pk_mul_f32 v[38:39], v[38:39], v[230:231] op_sel_hi:[1,0]
	v_pk_mul_f32 v[4:5], v[4:5], v[252:253] op_sel_hi:[1,0]
	v_pk_mul_f32 v[6:7], v[6:7], v[252:253] op_sel_hi:[1,0]
	s_waitcnt lgkmcnt(6)
	v_mfma_f32_16x16x32_bf16 v[32:35], v[208:211], v[132:135], v[32:35]
	v_mfma_f32_16x16x32_bf16 v[0:3], v[208:211], v[148:151], v[0:3]
	v_add_u32_e32 v172, 0xa300, v174
	ds_read2_b64 v[208:211], v172 offset1:4
	v_pk_mul_f32 v[40:41], v[40:41], v[230:231] op_sel_hi:[1,0]
	v_pk_mul_f32 v[42:43], v[42:43], v[230:231] op_sel_hi:[1,0]
	v_pk_mul_f32 v[8:9], v[8:9], v[252:253] op_sel_hi:[1,0]
	v_pk_mul_f32 v[10:11], v[10:11], v[252:253] op_sel_hi:[1,0]
	v_pk_add_f32 v[140:141], v[140:141], v[244:245] op_sel:[0,1] op_sel_hi:[1,1] neg_lo:[0,1] neg_hi:[0,1]
	v_pk_add_f32 v[152:153], v[152:153], v[246:247] op_sel_hi:[1,0] neg_lo:[0,1] neg_hi:[0,1]
	v_pk_add_f32 v[142:143], v[142:143], v[244:245] op_sel:[0,1] op_sel_hi:[1,1] neg_lo:[0,1] neg_hi:[0,1]
	v_pk_add_f32 v[154:155], v[154:155], v[246:247] op_sel_hi:[1,0] neg_lo:[0,1] neg_hi:[0,1]
	v_pk_add_f32 v[144:145], v[144:145], v[244:245] op_sel:[0,1] op_sel_hi:[1,1] neg_lo:[0,1] neg_hi:[0,1]
	v_pk_add_f32 v[160:161], v[160:161], v[246:247] op_sel_hi:[1,0] neg_lo:[0,1] neg_hi:[0,1]
	s_waitcnt lgkmcnt(6)
	v_mfma_f32_16x16x32_bf16 v[36:39], v[212:215], v[132:135], v[36:39]
	v_mfma_f32_16x16x32_bf16 v[4:7], v[212:215], v[148:151], v[4:7]
	v_add_u32_e32 v173, 0x6400, v174
	ds_read2_b64 v[212:215], v173 offset0:8 offset1:12
	v_pk_mul_f32 v[44:45], v[44:45], v[230:231] op_sel_hi:[1,0]
	v_pk_mul_f32 v[46:47], v[46:47], v[230:231] op_sel_hi:[1,0]
	v_pk_mul_f32 v[12:13], v[12:13], v[252:253] op_sel_hi:[1,0]
	v_pk_mul_f32 v[14:15], v[14:15], v[252:253] op_sel_hi:[1,0]
	v_pk_add_f32 v[146:147], v[146:147], v[244:245] op_sel:[0,1] op_sel_hi:[1,1] neg_lo:[0,1] neg_hi:[0,1]
	v_pk_add_f32 v[162:163], v[162:163], v[246:247] op_sel_hi:[1,0] neg_lo:[0,1] neg_hi:[0,1]
	v_exp_f32_e32 v140, v140
	v_exp_f32_e32 v152, v152
	v_exp_f32_e32 v141, v141
	v_exp_f32_e32 v153, v153
	s_waitcnt lgkmcnt(6)
; #define LAS __attribute__((address_space(3)))
; __device__ __forceinline__ unsigned cvt_pk_bf16(float lo, float hi) { unsigned r; asm("v_cvt_pk_bf16_f32 %0, %1, %2" : "=v"(r) : "v"(lo), "v"(hi)); return r; }
; __device__ __forceinline__ void attn_phase(LAS unsigned char* lds, const bf16_t* Q, const bf16_t* KN, const bf16_t* P, const bf16_t* VT, bf16_t* CAT, int bid, int G, const int tid) {
;     ...
;                     for (int kb = 0; kb < 4; ++kb)
; #pragma unroll
;                         for (int j = 0; j < 4; ++j) { const float e = __builtin_amdgcn_exp2f(s[kb][qi][j] - mnew); s[kb][qi][j] = e; ps += e; }
;                     lrow[qi] = lrow[qi] * alpha + ps;
; #pragma unroll
;                     for (int d = 0; d < 8; ++d) o[d][qi] = o[d][qi] * alpha;
; #pragma unroll
;                     for (int cc = 0; cc < 2; ++cc) {
;                         u32x4 t; t.x = cvt_pk_bf16(s[2 * cc][qi][0], s[2 * cc][qi][1]); t.y = cvt_pk_bf16(s[2 * cc][qi][2], s[2 * cc][qi][3]);
;                         t.z = cvt_pk_bf16(s[2 * cc + 1][qi][0], s[2 * cc + 1][qi][1]); t.w = cvt_pk_bf16(s[2 * cc + 1][qi][2], s[2 * cc + 1][qi][3]);
;                         pf[qi][cc] = __builtin_bit_cast(bf16x8, t);
;                     }
;                 }
; #pragma unroll
;                 for (int cc = 0; cc < 2; ++cc)
; #pragma unroll
;                     for (int d = 0; d < 8; ++d) {
;                         const LAS unsigned char* vp = buf + KBYTES + ((d * 16 + fr) * VS + 32 * cc + 4 * fq) * 2;
;                         const u32x2 v0 = *(const LAS u32x2*)vp, v1 = *(const LAS u32x2*)(vp + 32);
;                         const u32x4 vv = {v0.x, v0.y, v1.x, v1.y};
;                         const bf16x8 vf = __builtin_bit_cast(bf16x8, vv);
;                         o[d][0] = __builtin_amdgcn_mfma_f32_16x16x32_bf16(vf, pf[0][cc], o[d][0], 0, 0, 0);
;                         o[d][1] = __builtin_amdgcn_mfma_f32_16x16x32_bf16(vf, pf[1][cc], o[d][1], 0, 0, 0);
	v_mfma_f32_16x16x32_bf16 v[40:43], v[216:219], v[132:135], v[40:43]
	v_mfma_f32_16x16x32_bf16 v[8:11], v[216:219], v[148:151], v[8:11]
	v_add_u32_e32 v175, 0x6d00, v174
	ds_read2_b64 v[216:219], v175 offset0:8 offset1:12
	v_pk_mul_f32 v[52:53], v[52:53], v[230:231] op_sel_hi:[1,0]
	v_pk_mul_f32 v[54:55], v[54:55], v[230:231] op_sel_hi:[1,0]
	v_pk_mul_f32 v[16:17], v[16:17], v[252:253] op_sel_hi:[1,0]
	v_pk_mul_f32 v[18:19], v[18:19], v[252:253] op_sel_hi:[1,0]
	v_exp_f32_e32 v142, v142
	v_exp_f32_e32 v154, v154
	v_exp_f32_e32 v143, v143
	v_exp_f32_e32 v155, v155
	v_exp_f32_e32 v144, v144
	v_exp_f32_e32 v160, v160
	s_waitcnt lgkmcnt(6)
	v_mfma_f32_16x16x32_bf16 v[44:47], v[220:223], v[132:135], v[44:47]
	v_mfma_f32_16x16x32_bf16 v[12:15], v[220:223], v[148:151], v[12:15]
	v_add_u32_e32 v172, 0x7600, v174
	ds_read2_b64 v[220:223], v172 offset0:8 offset1:12
	v_pk_mul_f32 v[48:49], v[48:49], v[230:231] op_sel_hi:[1,0]
	v_pk_mul_f32 v[50:51], v[50:51], v[230:231] op_sel_hi:[1,0]
	v_pk_mul_f32 v[20:21], v[20:21], v[252:253] op_sel_hi:[1,0]
	v_pk_mul_f32 v[22:23], v[22:23], v[252:253] op_sel_hi:[1,0]
	v_exp_f32_e32 v145, v145
	v_exp_f32_e32 v161, v161
	v_exp_f32_e32 v146, v146
	v_exp_f32_e32 v162, v162
	v_exp_f32_e32 v147, v147
	v_exp_f32_e32 v163, v163
	s_waitcnt lgkmcnt(6)
	v_mfma_f32_16x16x32_bf16 v[52:55], v[224:227], v[132:135], v[52:55]
	v_mfma_f32_16x16x32_bf16 v[16:19], v[224:227], v[148:151], v[16:19]
	v_add_u32_e32 v173, 0x7f00, v174
	ds_read2_b64 v[224:227], v173 offset0:8 offset1:12
	v_pk_mul_f32 v[56:57], v[56:57], v[230:231] op_sel_hi:[1,0]
	v_pk_mul_f32 v[58:59], v[58:59], v[230:231] op_sel_hi:[1,0]
	v_pk_mul_f32 v[24:25], v[24:25], v[252:253] op_sel_hi:[1,0]
	v_pk_mul_f32 v[26:27], v[26:27], v[252:253] op_sel_hi:[1,0]
	v_pk_add_f32 v[228:229], v[228:229], v[140:141]
	v_pk_add_f32 v[170:171], v[170:171], v[152:153]
	v_pk_add_f32 v[228:229], v[228:229], v[142:143]
	v_pk_add_f32 v[170:171], v[170:171], v[154:155]
	v_pk_add_f32 v[228:229], v[228:229], v[144:145]
	v_pk_add_f32 v[170:171], v[170:171], v[160:161]
	s_waitcnt lgkmcnt(6)
	v_mfma_f32_16x16x32_bf16 v[48:51], v[136:139], v[132:135], v[48:51]
	v_mfma_f32_16x16x32_bf16 v[20:23], v[136:139], v[148:151], v[20:23]
	v_add_u32_e32 v175, 0x8800, v174
	ds_read2_b64 v[136:139], v175 offset0:8 offset1:12
	v_pk_mul_f32 v[60:61], v[60:61], v[230:231] op_sel_hi:[1,0]
	v_pk_mul_f32 v[62:63], v[62:63], v[230:231] op_sel_hi:[1,0]
	v_pk_mul_f32 v[28:29], v[28:29], v[252:253] op_sel_hi:[1,0]
	v_pk_mul_f32 v[30:31], v[30:31], v[252:253] op_sel_hi:[1,0]
	v_pk_add_f32 v[228:229], v[228:229], v[146:147]
	v_pk_add_f32 v[170:171], v[170:171], v[162:163]
	v_add_f32_e32 v228, v228, v229
	v_add_f32_e32 v170, v170, v171
	v_cvt_pk_bf16_f32 v140, v140, v141
	v_cvt_pk_bf16_f32 v141, v142, v143
	s_waitcnt lgkmcnt(6)
	v_mfma_f32_16x16x32_bf16 v[56:59], v[156:159], v[132:135], v[56:59]
	v_mfma_f32_16x16x32_bf16 v[24:27], v[156:159], v[148:151], v[24:27]
	v_add_u32_e32 v172, 0x9100, v174
	ds_read2_b64 v[156:159], v172 offset0:8 offset1:12
	v_cvt_pk_bf16_f32 v142, v144, v145
	v_cvt_pk_bf16_f32 v143, v146, v147
	v_cvt_pk_bf16_f32 v152, v152, v153
	v_cvt_pk_bf16_f32 v153, v154, v155
	v_cvt_pk_bf16_f32 v154, v160, v161
	v_cvt_pk_bf16_f32 v155, v162, v163
	s_waitcnt lgkmcnt(6)
	v_mfma_f32_16x16x32_bf16 v[60:63], v[208:211], v[132:135], v[60:63]
	v_mfma_f32_16x16x32_bf16 v[28:31], v[208:211], v[148:151], v[28:31]
	v_add_u32_e32 v173, 0x9a00, v174
	ds_read2_b64 v[208:211], v173 offset0:8 offset1:12
	v_fma_f32 v203, v203, v230, v228
	v_fma_f32 v202, v202, v252, v170
	v_mov_b32_e32 v207, v245
	v_mov_b32_e32 v206, v246
	s_waitcnt lgkmcnt(6)
	v_mfma_f32_16x16x32_bf16 v[32:35], v[212:215], v[140:143], v[32:35]
	v_mfma_f32_16x16x32_bf16 v[0:3], v[212:215], v[152:155], v[0:3]
	v_add_u32_e32 v175, 0xa300, v174
	ds_read2_b64 v[212:215], v175 offset0:8 offset1:12
	s_waitcnt lgkmcnt(6)
	v_mfma_f32_16x16x32_bf16 v[36:39], v[216:219], v[140:143], v[36:39]
	v_mfma_f32_16x16x32_bf16 v[4:7], v[216:219], v[152:155], v[4:7]
	s_waitcnt lgkmcnt(5)
	v_mfma_f32_16x16x32_bf16 v[40:43], v[220:223], v[140:143], v[40:43]
	v_mfma_f32_16x16x32_bf16 v[8:11], v[220:223], v[152:155], v[8:11]
	s_waitcnt lgkmcnt(4)
	v_mfma_f32_16x16x32_bf16 v[44:47], v[224:227], v[140:143], v[44:47]
	v_mfma_f32_16x16x32_bf16 v[12:15], v[224:227], v[152:155], v[12:15]
	s_waitcnt lgkmcnt(3)
	v_mfma_f32_16x16x32_bf16 v[52:55], v[136:139], v[140:143], v[52:55]
	v_mfma_f32_16x16x32_bf16 v[16:19], v[136:139], v[152:155], v[16:19]
	s_waitcnt lgkmcnt(2)
	v_mfma_f32_16x16x32_bf16 v[48:51], v[156:159], v[140:143], v[48:51]
	v_mfma_f32_16x16x32_bf16 v[20:23], v[156:159], v[152:155], v[20:23]
	s_waitcnt lgkmcnt(1)
	v_mfma_f32_16x16x32_bf16 v[56:59], v[208:211], v[140:143], v[56:59]
	v_mfma_f32_16x16x32_bf16 v[24:27], v[208:211], v[152:155], v[24:27]
	s_waitcnt lgkmcnt(0)
	v_mfma_f32_16x16x32_bf16 v[60:63], v[212:215], v[140:143], v[60:63]
	v_mfma_f32_16x16x32_bf16 v[28:31], v[212:215], v[152:155], v[28:31]
; #define LAS __attribute__((address_space(3)))
; __device__ __forceinline__ void attn_phase(LAS unsigned char* lds, const bf16_t* Q, const bf16_t* KN, const bf16_t* P, const bf16_t* VT, bf16_t* CAT, int bid, int G, const int tid) {
;     ...
;         for (int kt = 0; kt < nt; ++kt) {
;             LAS unsigned char* buf = lds + (kt & 1) * BUFB;
;             *(LAS u32x4*)(buf + lk) = rk0; *(LAS u32x4*)(buf + lk + 32 * KS * 2) = rk1; *(LAS u32x4*)(buf + lp) = rp;
;             *(LAS u32x4*)(buf + lv) = rv0; *(LAS u32x4*)(buf + lv + 64 * VS * 2) = rv1;
;             __syncthreads();
;             if (kt + 1 < nt) {
;                 const size_t ko = (size_t)(kt + 1) * 64;
;                 rk0 = *(const u32x4*)(gk + ko * 1024); rk1 = *(const u32x4*)(gk + (ko + 32) * 1024); rp = *(const u32x4*)(gp + ko * P_LD);
;                 rv0 = *(const u32x4*)(gv + ko); rv1 = *(const u32x4*)(gv + (size_t)64 * M + ko);
;             }
.LBB0_145:
	s_cmp_lg_u32 s80, 0
	s_cbranch_scc1 .Lat_end_now
	s_bitcmp0_b32 s34, 0
	s_cselect_b32 s4, 0xac00, 0
	v_add_u32_e32 v228, s4, v183
	s_waitcnt vmcnt(0) lgkmcnt(0)
	ds_write_b128 v228, v[112:115]
	ds_write_b128 v228, v[116:119] offset:12800
	v_add_u32_e32 v229, s4, v240
	ds_write_b128 v229, v[120:123]
	v_add_u32_e32 v228, s4, v241
	ds_write_b128 v228, v[124:127] offset:25600
	ds_write_b128 v228, v[128:131] offset:34816
	s_add_i32 s4, s30, 0x80
	s_cmp_gt_i32 s4, s31
	s_cbranch_scc1 .Lat_nog_end
	v_lshl_add_u64 v[112:113], s[24:25], 0, v[166:167]
	s_mov_b32 s4, 0x1c220000
	v_add_co_u32_e32 v114, vcc, s4, v112
	s_mov_b32 s4, 0x1c230000
	s_nop 0
	v_addc_co_u32_e32 v115, vcc, 0, v113, vcc
	v_add_co_u32_e32 v116, vcc, s4, v112
	v_lshl_add_u64 v[128:129], s[24:25], 0, v[168:169]
	s_nop 0
	v_addc_co_u32_e32 v117, vcc, 0, v113, vcc
	v_add_co_u32_e32 v124, vcc, 0x20200000, v128
	v_lshl_add_u64 v[120:121], s[24:25], 0, v[164:165]
	s_nop 0
	v_addc_co_u32_e32 v125, vcc, 0, v129, vcc
	v_add_co_u32_e32 v128, vcc, 0x20600000, v128
	s_waitcnt lgkmcnt(0)
	s_nop 0
	v_addc_co_u32_e32 v129, vcc, 0, v129, vcc
	s_nop 0
	global_load_dwordx4 v[112:115], v[114:115], off
	s_nop 0
	global_load_dwordx4 v[116:119], v[116:117], off
	s_nop 0
	global_load_dwordx4 v[120:123], v[120:121], off
	s_nop 0
	global_load_dwordx4 v[124:127], v[124:125], off offset:128
	global_load_dwordx4 v[128:131], v[128:129], off offset:128
.Lat_nog_end:
.Lat_end_now:
	s_mov_b64 s[4:5], 0x68000
	s_add_i32 s30, s30, 64
	v_lshl_add_u64 v[164:165], v[164:165], 0, s[4:5]
	s_mov_b64 s[4:5], 0x20000
	s_add_i32 s34, s34, 1
	v_lshl_add_u64 v[166:167], v[166:167], 0, s[4:5]
	s_cmp_eq_u32 s31, s30
	v_lshl_add_u64 v[168:169], v[168:169], 0, s[22:23]
	s_cbranch_scc1 .LBB0_149
.LBB0_146:
	s_bitcmp1_b32 s34, 0
	s_cselect_b32 s4, 0xac00, 0
	s_add_i32 s35, s4, 0
	s_waitcnt lgkmcnt(0)
	s_barrier
	s_cmp_gt_i32 s30, s26
	s_cbranch_scc1 .Lat_mid
	v_add3_u32 v174, s35, v182, v181
	ds_read_b128 v[170:173], v174
	ds_read_b128 v[208:211], v174 offset:6400
	ds_read_b128 v[212:215], v174 offset:12800
	ds_read_b128 v[216:219], v174 offset:19200
	ds_read_b128 v[220:223], v174 offset:64
	ds_read_b128 v[224:227], v174 offset:6464
	s_add_i32 s4, s30, 63
	s_cmp_le_i32 s4, s21
	s_waitcnt lgkmcnt(5)
	v_mfma_f32_16x16x32_bf16 v[132:135], v[170:173], v[104:107], 0
	v_mfma_f32_16x16x32_bf16 v[148:151], v[170:173], v[108:111], 0
	ds_read_b128 v[170:173], v174 offset:12864
	s_waitcnt lgkmcnt(5)
	v_mfma_f32_16x16x32_bf16 v[136:139], v[208:211], v[104:107], 0
	v_mfma_f32_16x16x32_bf16 v[156:159], v[208:211], v[108:111], 0
	ds_read_b128 v[208:211], v174 offset:19264
	s_waitcnt lgkmcnt(5)
	v_mfma_f32_16x16x32_bf16 v[140:143], v[212:215], v[104:107], 0
	v_mfma_f32_16x16x32_bf16 v[152:155], v[212:215], v[108:111], 0
	ds_read_b128 v[212:215], v174 offset:128
	s_waitcnt lgkmcnt(5)
	v_mfma_f32_16x16x32_bf16 v[144:147], v[216:219], v[104:107], 0
	v_mfma_f32_16x16x32_bf16 v[160:163], v[216:219], v[108:111], 0
	ds_read_b128 v[216:219], v174 offset:6528
	s_waitcnt lgkmcnt(5)
	v_mfma_f32_16x16x32_bf16 v[132:135], v[220:223], v[92:95], v[132:135]
	v_mfma_f32_16x16x32_bf16 v[148:151], v[220:223], v[100:103], v[148:151]
	ds_read_b128 v[220:223], v174 offset:12928
	s_waitcnt lgkmcnt(5)
	v_mfma_f32_16x16x32_bf16 v[136:139], v[224:227], v[92:95], v[136:139]
	v_mfma_f32_16x16x32_bf16 v[156:159], v[224:227], v[100:103], v[156:159]
	ds_read_b128 v[224:227], v174 offset:19328
	s_waitcnt lgkmcnt(5)
	v_mfma_f32_16x16x32_bf16 v[140:143], v[170:173], v[92:95], v[140:143]
	v_mfma_f32_16x16x32_bf16 v[152:155], v[170:173], v[100:103], v[152:155]
	ds_read_b128 v[170:173], v174 offset:192
	s_waitcnt lgkmcnt(5)
	v_mfma_f32_16x16x32_bf16 v[144:147], v[208:211], v[92:95], v[144:147]
	v_mfma_f32_16x16x32_bf16 v[160:163], v[208:211], v[100:103], v[160:163]
	ds_read_b128 v[208:211], v174 offset:6592
	s_waitcnt lgkmcnt(5)
	v_mfma_f32_16x16x32_bf16 v[132:135], v[212:215], v[88:91], v[132:135]
	v_mfma_f32_16x16x32_bf16 v[148:151], v[212:215], v[96:99], v[148:151]
	ds_read_b128 v[212:215], v174 offset:12992
	s_waitcnt lgkmcnt(5)
	v_mfma_f32_16x16x32_bf16 v[136:139], v[216:219], v[88:91], v[136:139]
	v_mfma_f32_16x16x32_bf16 v[156:159], v[216:219], v[96:99], v[156:159]
	ds_read_b128 v[216:219], v174 offset:19392
	s_waitcnt lgkmcnt(5)
	v_mfma_f32_16x16x32_bf16 v[140:143], v[220:223], v[88:91], v[140:143]
	v_mfma_f32_16x16x32_bf16 v[152:155], v[220:223], v[96:99], v[152:155]
	ds_read_b128 v[220:223], v174 offset:256
	s_waitcnt lgkmcnt(5)
	v_mfma_f32_16x16x32_bf16 v[144:147], v[224:227], v[88:91], v[144:147]
	v_mfma_f32_16x16x32_bf16 v[160:163], v[224:227], v[96:99], v[160:163]
	ds_read_b128 v[224:227], v174 offset:6656
	s_waitcnt lgkmcnt(5)
	v_mfma_f32_16x16x32_bf16 v[132:135], v[170:173], v[76:79], v[132:135]
	v_mfma_f32_16x16x32_bf16 v[148:151], v[170:173], v[84:87], v[148:151]
	ds_read_b128 v[170:173], v174 offset:13056
	s_waitcnt lgkmcnt(5)
	v_mfma_f32_16x16x32_bf16 v[136:139], v[208:211], v[76:79], v[136:139]
	v_mfma_f32_16x16x32_bf16 v[156:159], v[208:211], v[84:87], v[156:159]
	ds_read_b128 v[208:211], v174 offset:19456
	s_waitcnt lgkmcnt(5)
	v_mfma_f32_16x16x32_bf16 v[140:143], v[212:215], v[76:79], v[140:143]
	v_mfma_f32_16x16x32_bf16 v[152:155], v[212:215], v[84:87], v[152:155]
	ds_read_b128 v[212:215], v174 offset:320
	s_waitcnt lgkmcnt(5)
	v_mfma_f32_16x16x32_bf16 v[144:147], v[216:219], v[76:79], v[144:147]
	v_mfma_f32_16x16x32_bf16 v[160:163], v[216:219], v[84:87], v[160:163]
	ds_read_b128 v[216:219], v174 offset:6720
	s_waitcnt lgkmcnt(5)
	v_mfma_f32_16x16x32_bf16 v[132:135], v[220:223], v[72:75], v[132:135]
	v_mfma_f32_16x16x32_bf16 v[148:151], v[220:223], v[80:83], v[148:151]
	ds_read_b128 v[220:223], v174 offset:13120
	s_waitcnt lgkmcnt(5)
	v_mfma_f32_16x16x32_bf16 v[136:139], v[224:227], v[72:75], v[136:139]
	v_mfma_f32_16x16x32_bf16 v[156:159], v[224:227], v[80:83], v[156:159]
	ds_read_b128 v[224:227], v174 offset:19520
	s_waitcnt lgkmcnt(5)
	v_mfma_f32_16x16x32_bf16 v[140:143], v[170:173], v[72:75], v[140:143]
	v_mfma_f32_16x16x32_bf16 v[152:155], v[170:173], v[80:83], v[152:155]
	s_waitcnt lgkmcnt(4)
	v_mfma_f32_16x16x32_bf16 v[144:147], v[208:211], v[72:75], v[144:147]
	v_mfma_f32_16x16x32_bf16 v[160:163], v[208:211], v[80:83], v[160:163]
	s_waitcnt lgkmcnt(3)
	v_mfma_f32_16x16x32_bf16 v[132:135], v[212:215], v[64:67], v[132:135]
	v_mfma_f32_16x16x32_bf16 v[148:151], v[212:215], v[68:71], v[148:151]
	s_waitcnt lgkmcnt(2)
	v_mfma_f32_16x16x32_bf16 v[136:139], v[216:219], v[64:67], v[136:139]
	v_mfma_f32_16x16x32_bf16 v[156:159], v[216:219], v[68:71], v[156:159]
	s_waitcnt lgkmcnt(1)
	v_mfma_f32_16x16x32_bf16 v[140:143], v[220:223], v[64:67], v[140:143]
	v_mfma_f32_16x16x32_bf16 v[152:155], v[220:223], v[68:71], v[152:155]
	s_waitcnt lgkmcnt(0)
	v_mfma_f32_16x16x32_bf16 v[144:147], v[224:227], v[64:67], v[144:147]
	v_mfma_f32_16x16x32_bf16 v[160:163], v[224:227], v[68:71], v[160:163]
	s_cbranch_scc1 .Lat_mid
; #define LAS __attribute__((address_space(3)))
; __device__ __forceinline__ void attn_phase(LAS unsigned char* lds, const bf16_t* Q, const bf16_t* KN, const bf16_t* P, const bf16_t* VT, bf16_t* CAT, int bid, int G, const int tid) {
;     ...
;             *(LAS u32x4*)(buf + lk) = rk0; *(LAS u32x4*)(buf + lk + 32 * KS * 2) = rk1; *(LAS u32x4*)(buf + lp) = rp;
;             *(LAS u32x4*)(buf + lv) = rv0; *(LAS u32x4*)(buf + lv + 64 * VS * 2) = rv1;
;             __syncthreads();
;             if (kt + 1 < nt) {
;                 const size_t ko = (size_t)(kt + 1) * 64;
;                 rk0 = *(const u32x4*)(gk + ko * 1024); rk1 = *(const u32x4*)(gk + (ko + 32) * 1024); rp = *(const u32x4*)(gp + ko * P_LD);
;                 rv0 = *(const u32x4*)(gv + ko); rv1 = *(const u32x4*)(gv + (size_t)64 * M + ko);
;             }
;     ...
;                 if (kt * 64 + 63 > qlo) {
; #pragma unroll
;                     for (int kb = 0; kb < 4; ++kb)
; #pragma unroll
;                         for (int qi = 0; qi < 2; ++qi)
; #pragma unroll
;                             for (int j = 0; j < 4; ++j) { const int key = kt * 64 + kb * 16 + fq * 4 + j, q = qlo + qi * 16 + fr; if (key > q) s[kb][qi][j] = -INFINITY; }
;                 }
	v_add_u32_e32 v171, s30, v242
	v_cmp_gt_i32_e32 vcc, v171, v244
	v_mov_b32_e32 v170, s78
	v_cmp_lt_i32_e64 s[4:5], v171, v244
	v_cndmask_b32_e32 v170, v132, v170, vcc
	v_add_u32_e32 v172, 2, v171
	v_cndmask_b32_e64 v132, v170, v132, s[4:5]
	v_cndmask_b32_e64 v133, v234, v133, s[4:5]
	v_cmp_le_i32_e64 s[4:5], v172, v244
	v_add_u32_e32 v173, 3, v171
	v_mov_b32_e32 v170, s78
	v_cndmask_b32_e64 v134, v234, v134, s[4:5]
	v_cmp_le_i32_e64 s[4:5], v173, v244
	v_add_u32_e32 v174, 19, v171
	v_add_u32_e32 v175, 35, v171
	v_cndmask_b32_e64 v135, v234, v135, s[4:5]
	v_cmp_gt_i32_e64 s[4:5], v171, v199
	s_nop 1
	v_cndmask_b32_e64 v170, v148, v170, s[4:5]
	v_cmp_lt_i32_e64 s[4:5], v171, v199
	s_nop 1
	v_cndmask_b32_e64 v148, v170, v148, s[4:5]
	v_cndmask_b32_e64 v149, v234, v149, s[4:5]
	v_cmp_le_i32_e64 s[4:5], v172, v199
	v_add_u32_e32 v170, 16, v171
	v_add_u32_e32 v172, 17, v171
	v_cndmask_b32_e64 v150, v234, v150, s[4:5]
	v_cmp_le_i32_e64 s[4:5], v173, v199
	v_add_u32_e32 v173, 18, v171
	s_nop 0
	v_cndmask_b32_e64 v151, v234, v151, s[4:5]
	v_cmp_gt_i32_e64 s[4:5], v170, v244
	v_mov_b32_e32 v170, s78
	v_cndmask_b32_e32 v156, v156, v170, vcc
	v_cmp_le_i32_e32 vcc, v172, v199
	v_cndmask_b32_e64 v136, v136, v170, s[4:5]
	v_cmp_le_i32_e64 s[4:5], v172, v244
	v_cndmask_b32_e32 v157, v234, v157, vcc
	v_cmp_le_i32_e32 vcc, v173, v199
	v_add_u32_e32 v172, 32, v171
	v_cndmask_b32_e64 v137, v234, v137, s[4:5]
	v_cndmask_b32_e32 v158, v234, v158, vcc
	v_cmp_le_i32_e32 vcc, v174, v199
	v_cmp_le_i32_e64 s[4:5], v173, v244
	v_add_u32_e32 v173, 33, v171
	v_cndmask_b32_e32 v159, v234, v159, vcc
	v_cmp_gt_i32_e32 vcc, v172, v244
	v_cndmask_b32_e64 v138, v234, v138, s[4:5]
	v_cmp_le_i32_e64 s[4:5], v174, v244
	v_cndmask_b32_e32 v140, v140, v170, vcc
	v_cmp_le_i32_e32 vcc, v173, v244
	v_add_u32_e32 v174, 34, v171
	v_cndmask_b32_e64 v139, v234, v139, s[4:5]
	v_cndmask_b32_e32 v141, v234, v141, vcc
	v_cmp_le_i32_e32 vcc, v174, v244
	s_nop 1
	v_cndmask_b32_e32 v142, v234, v142, vcc
	v_cmp_le_i32_e32 vcc, v175, v244
	s_nop 1
	v_cndmask_b32_e32 v143, v234, v143, vcc
	v_cmp_gt_i32_e32 vcc, v172, v199
	v_add_u32_e32 v172, 48, v171
	s_nop 0
	v_cndmask_b32_e32 v152, v152, v170, vcc
	v_cmp_le_i32_e32 vcc, v173, v199
	v_add_u32_e32 v173, 49, v171
	s_nop 0
	v_cndmask_b32_e32 v153, v234, v153, vcc
	v_cmp_le_i32_e32 vcc, v174, v199
	v_add_u32_e32 v174, 50, v171
	v_add_u32_e32 v171, 51, v171
	v_cndmask_b32_e32 v154, v234, v154, vcc
	v_cmp_le_i32_e32 vcc, v175, v199
	s_nop 1
	v_cndmask_b32_e32 v155, v234, v155, vcc
	v_cmp_gt_i32_e32 vcc, v172, v244
	s_nop 1
	v_cndmask_b32_e32 v144, v144, v170, vcc
	v_cmp_le_i32_e32 vcc, v173, v244
	s_nop 1
	v_cndmask_b32_e32 v145, v234, v145, vcc
	v_cmp_le_i32_e32 vcc, v174, v244
	s_nop 1
	v_cndmask_b32_e32 v146, v234, v146, vcc
	v_cmp_le_i32_e32 vcc, v171, v244
	s_nop 1
	v_cndmask_b32_e32 v147, v234, v147, vcc
	v_cmp_gt_i32_e32 vcc, v172, v199
	s_nop 1
	v_cndmask_b32_e32 v160, v160, v170, vcc
	v_cmp_le_i32_e32 vcc, v173, v199
	s_nop 1
	v_cndmask_b32_e32 v161, v234, v161, vcc
	v_cmp_le_i32_e32 vcc, v174, v199
	s_nop 1
	v_cndmask_b32_e32 v162, v234, v162, vcc
	v_cmp_le_i32_e32 vcc, v171, v199
	s_nop 1
	v_cndmask_b32_e32 v163, v234, v163, vcc
.Lat_mid:
	s_cmp_eq_u32 s80, 0
	s_cbranch_scc1 .Lat_mid_bar
	s_bitcmp0_b32 s34, 0
	s_cselect_b32 s4, 0xac00, 0
	v_add_u32_e32 v228, s4, v183
	s_waitcnt vmcnt(0) lgkmcnt(0)
	ds_write_b128 v228, v[112:115]
	ds_write_b128 v228, v[116:119] offset:12800
	v_add_u32_e32 v229, s4, v240
	ds_write_b128 v229, v[120:123]
	v_add_u32_e32 v228, s4, v241
	ds_write_b128 v228, v[124:127] offset:25600
	ds_write_b128 v228, v[128:131] offset:34816
	s_add_i32 s4, s30, 0x80
	s_cmp_gt_i32 s4, s31
	s_cbranch_scc1 .Lat_nog_mid
	v_lshl_add_u64 v[112:113], s[24:25], 0, v[166:167]
	s_mov_b32 s4, 0x1c220000
	v_add_co_u32_e32 v114, vcc, s4, v112
	s_mov_b32 s4, 0x1c230000
	s_nop 0
	v_addc_co_u32_e32 v115, vcc, 0, v113, vcc
	v_add_co_u32_e32 v116, vcc, s4, v112
	v_lshl_add_u64 v[128:129], s[24:25], 0, v[168:169]
	s_nop 0
	v_addc_co_u32_e32 v117, vcc, 0, v113, vcc
	v_add_co_u32_e32 v124, vcc, 0x20200000, v128
	v_lshl_add_u64 v[120:121], s[24:25], 0, v[164:165]
	s_nop 0
	v_addc_co_u32_e32 v125, vcc, 0, v129, vcc
	v_add_co_u32_e32 v128, vcc, 0x20600000, v128
	s_waitcnt lgkmcnt(0)
	s_nop 0
	v_addc_co_u32_e32 v129, vcc, 0, v129, vcc
	s_nop 0
	global_load_dwordx4 v[112:115], v[114:115], off
	s_nop 0
	global_load_dwordx4 v[116:119], v[116:117], off
	s_nop 0
	global_load_dwordx4 v[120:123], v[120:121], off
	s_nop 0
	global_load_dwordx4 v[124:127], v[124:125], off offset:128
	global_load_dwordx4 v[128:131], v[128:129], off offset:128
.Lat_nog_mid:
.Lat_mid_bar:
	s_waitcnt lgkmcnt(0)
	s_barrier
	s_cmp_gt_i32 s30, s26
	s_cbranch_scc1 .LBB0_145
	s_branch .LBB0_144
; #define LAS __attribute__((address_space(3)))
; __device__ __forceinline__ void attn_phase(LAS unsigned char* lds, const bf16_t* Q, const bf16_t* KN, const bf16_t* P, const bf16_t* VT, bf16_t* CAT, int bid, int G, const int tid) {
;     ...
;         for (int kt = 0; kt < nt; ++kt) {
;             LAS unsigned char* buf = lds + (kt & 1) * BUFB;
;             *(LAS u32x4*)(buf + lk) = rk0; *(LAS u32x4*)(buf + lk + 32 * KS * 2) = rk1; *(LAS u32x4*)(buf + lp) = rp;
;             *(LAS u32x4*)(buf + lv) = rv0; *(LAS u32x4*)(buf + lv + 64 * VS * 2) = rv1;
;             __syncthreads();
;             if (kt + 1 < nt) {
;                 const size_t ko = (size_t)(kt + 1) * 64;
;                 rk0 = *(const u32x4*)(gk + ko * 1024); rk1 = *(const u32x4*)(gk + (ko + 32) * 1024); rp = *(const u32x4*)(gp + ko * P_LD);
;                 rv0 = *(const u32x4*)(gv + ko); rv1 = *(const u32x4*)(gv + (size_t)64 * M + ko);
;             }
;             if (kt * 64 <= qlo + 31) {
;                 f32x4 s[4][2];
; #pragma unroll
;                 for (int kb = 0; kb < 4; ++kb) { s[kb][0] = (f32x4){0.f, 0.f, 0.f, 0.f}; s[kb][1] = (f32x4){0.f, 0.f, 0.f, 0.f}; }
; #pragma unroll
;                 for (int ch = 0; ch < 6; ++ch) {
; #pragma unroll
;                     for (int kb = 0; kb < 4; ++kb) {
;                         const bf16x8 kf = *(const LAS bf16x8*)(buf + ((kb * 16 + fr) * KS + ch * 32 + fq * 8) * 2);
;                         s[kb][0] = __builtin_amdgcn_mfma_f32_16x16x32_bf16(kf, qf[0][ch], s[kb][0], 0, 0, 0);
;                         s[kb][1] = __builtin_amdgcn_mfma_f32_16x16x32_bf16(kf, qf[1][ch], s[kb][1], 0, 0, 0);
;                     }
;                     if (ch & 1) asm volatile("" ::: "memory");
;                 }
.LBB0_149:
	s_bitcmp1_b32 s34, 0
	s_cselect_b32 s4, 0xac00, 0
	s_add_i32 s30, s4, 0
	s_lshl_b32 s31, s34, 6
	s_waitcnt lgkmcnt(0)
	s_barrier
	s_cmp_le_i32 s31, s26
	s_mov_b64 s[4:5], -1
	s_cbranch_scc0 .Lat_last_skip
	v_add3_u32 v140, s30, v182, v181
	ds_read_b128 v[112:115], v140
	ds_read_b128 v[120:123], v140 offset:6400
	ds_read_b128 v[128:131], v140 offset:12800
	ds_read_b128 v[136:139], v140 offset:19200
	s_or_b32 s4, s31, 63
	s_cmp_le_i32 s4, s21
	s_waitcnt lgkmcnt(3)
	v_mfma_f32_16x16x32_bf16 v[116:119], v[112:115], v[104:107], 0
	v_mfma_f32_16x16x32_bf16 v[112:115], v[112:115], v[108:111], 0
	s_waitcnt lgkmcnt(2)
	v_mfma_f32_16x16x32_bf16 v[124:127], v[120:123], v[104:107], 0
	v_mfma_f32_16x16x32_bf16 v[120:123], v[120:123], v[108:111], 0
	s_waitcnt lgkmcnt(1)
	v_mfma_f32_16x16x32_bf16 v[132:135], v[128:131], v[104:107], 0
	v_mfma_f32_16x16x32_bf16 v[128:131], v[128:131], v[108:111], 0
	s_waitcnt lgkmcnt(0)
	v_mfma_f32_16x16x32_bf16 v[104:107], v[136:139], v[104:107], 0
	v_mfma_f32_16x16x32_bf16 v[108:111], v[136:139], v[108:111], 0
	ds_read_b128 v[136:139], v140 offset:64
	s_waitcnt lgkmcnt(0)
	v_mfma_f32_16x16x32_bf16 v[116:119], v[136:139], v[92:95], v[116:119]
	v_mfma_f32_16x16x32_bf16 v[112:115], v[136:139], v[100:103], v[112:115]
	ds_read_b128 v[136:139], v140 offset:6464
	s_waitcnt lgkmcnt(0)
	v_mfma_f32_16x16x32_bf16 v[124:127], v[136:139], v[92:95], v[124:127]
	v_mfma_f32_16x16x32_bf16 v[120:123], v[136:139], v[100:103], v[120:123]
	ds_read_b128 v[136:139], v140 offset:12864
	s_waitcnt lgkmcnt(0)
	v_mfma_f32_16x16x32_bf16 v[132:135], v[136:139], v[92:95], v[132:135]
	v_mfma_f32_16x16x32_bf16 v[128:131], v[136:139], v[100:103], v[128:131]
	ds_read_b128 v[136:139], v140 offset:19264
	s_waitcnt lgkmcnt(0)
	v_mfma_f32_16x16x32_bf16 v[92:95], v[136:139], v[92:95], v[104:107]
	s_nop 2
	ds_read_b128 v[104:107], v140 offset:128
	v_mfma_f32_16x16x32_bf16 v[100:103], v[136:139], v[100:103], v[108:111]
	s_waitcnt lgkmcnt(0)
	v_mfma_f32_16x16x32_bf16 v[108:111], v[104:107], v[88:91], v[116:119]
	v_mfma_f32_16x16x32_bf16 v[104:107], v[104:107], v[96:99], v[112:115]
	s_nop 2
	ds_read_b128 v[112:115], v140 offset:6528
	s_waitcnt lgkmcnt(0)
	v_mfma_f32_16x16x32_bf16 v[116:119], v[112:115], v[88:91], v[124:127]
	v_mfma_f32_16x16x32_bf16 v[112:115], v[112:115], v[96:99], v[120:123]
	s_nop 2
	ds_read_b128 v[120:123], v140 offset:12928
	s_waitcnt lgkmcnt(0)
	v_mfma_f32_16x16x32_bf16 v[124:127], v[120:123], v[88:91], v[132:135]
	v_mfma_f32_16x16x32_bf16 v[120:123], v[120:123], v[96:99], v[128:131]
	s_nop 2
	ds_read_b128 v[128:131], v140 offset:19328
	s_waitcnt lgkmcnt(0)
	v_mfma_f32_16x16x32_bf16 v[88:91], v[128:131], v[88:91], v[92:95]
	v_mfma_f32_16x16x32_bf16 v[92:95], v[128:131], v[96:99], v[100:103]
	ds_read_b128 v[96:99], v140 offset:192
	s_waitcnt lgkmcnt(0)
	v_mfma_f32_16x16x32_bf16 v[100:103], v[96:99], v[76:79], v[108:111]
	v_mfma_f32_16x16x32_bf16 v[96:99], v[96:99], v[84:87], v[104:107]
	s_nop 2
	ds_read_b128 v[104:107], v140 offset:6592
	s_waitcnt lgkmcnt(0)
	v_mfma_f32_16x16x32_bf16 v[108:111], v[104:107], v[76:79], v[116:119]
	v_mfma_f32_16x16x32_bf16 v[104:107], v[104:107], v[84:87], v[112:115]
	s_nop 2
	ds_read_b128 v[112:115], v140 offset:12992
	s_waitcnt lgkmcnt(0)
	v_mfma_f32_16x16x32_bf16 v[116:119], v[112:115], v[76:79], v[124:127]
	v_mfma_f32_16x16x32_bf16 v[112:115], v[112:115], v[84:87], v[120:123]
	s_nop 2
	ds_read_b128 v[120:123], v140 offset:19392
	s_waitcnt lgkmcnt(0)
	v_mfma_f32_16x16x32_bf16 v[76:79], v[120:123], v[76:79], v[88:91]
	s_nop 2
	ds_read_b128 v[88:91], v140 offset:256
	v_mfma_f32_16x16x32_bf16 v[84:87], v[120:123], v[84:87], v[92:95]
	s_waitcnt lgkmcnt(0)
	v_mfma_f32_16x16x32_bf16 v[92:95], v[88:91], v[72:75], v[100:103]
	v_mfma_f32_16x16x32_bf16 v[88:91], v[88:91], v[80:83], v[96:99]
	s_nop 2
	ds_read_b128 v[96:99], v140 offset:6656
	s_waitcnt lgkmcnt(0)
	v_mfma_f32_16x16x32_bf16 v[100:103], v[96:99], v[72:75], v[108:111]
	s_nop 2
	ds_read_b128 v[108:111], v140 offset:19456
	v_mfma_f32_16x16x32_bf16 v[96:99], v[96:99], v[80:83], v[104:107]
	s_nop 2
	ds_read_b128 v[104:107], v140 offset:13056
	s_waitcnt lgkmcnt(0)
	v_mfma_f32_16x16x32_bf16 v[116:119], v[104:107], v[72:75], v[116:119]
	v_mfma_f32_16x16x32_bf16 v[104:107], v[104:107], v[80:83], v[112:115]
	v_mfma_f32_16x16x32_bf16 v[112:115], v[108:111], v[72:75], v[76:79]
	s_nop 2
	ds_read_b128 v[76:79], v140 offset:320
	v_mfma_f32_16x16x32_bf16 v[120:123], v[108:111], v[80:83], v[84:87]
	s_waitcnt lgkmcnt(0)
	v_mfma_f32_16x16x32_bf16 v[72:75], v[76:79], v[64:67], v[92:95]
	v_mfma_f32_16x16x32_bf16 v[108:111], v[76:79], v[68:71], v[88:91]
	ds_read_b128 v[76:79], v140 offset:6720
	s_nop 1
	ds_read_b128 v[88:91], v140 offset:13120
	s_waitcnt lgkmcnt(0)
	v_mfma_f32_16x16x32_bf16 v[84:87], v[88:91], v[64:67], v[116:119]
	v_mfma_f32_16x16x32_bf16 v[104:107], v[88:91], v[68:71], v[104:107]
	ds_read_b128 v[88:91], v140 offset:19520
	v_mfma_f32_16x16x32_bf16 v[80:83], v[76:79], v[64:67], v[100:103]
	v_mfma_f32_16x16x32_bf16 v[76:79], v[76:79], v[68:71], v[96:99]
	s_waitcnt lgkmcnt(0)
	v_mfma_f32_16x16x32_bf16 v[64:67], v[88:91], v[64:67], v[112:115]
	v_mfma_f32_16x16x32_bf16 v[116:119], v[88:91], v[68:71], v[120:123]
	s_cbranch_scc1 .LBB0_152
; __device__ __forceinline__ void attn_phase(LAS unsigned char* lds, const bf16_t* Q, const bf16_t* KN, const bf16_t* P, const bf16_t* VT, bf16_t* CAT, int bid, int G, const int tid) {
;     ...
;                 if (kt * 64 + 63 > qlo) {
; #pragma unroll
;                     for (int kb = 0; kb < 4; ++kb)
; #pragma unroll
;                         for (int qi = 0; qi < 2; ++qi)
; #pragma unroll
;                             for (int j = 0; j < 4; ++j) { const int key = kt * 64 + kb * 16 + fq * 4 + j, q = qlo + qi * 16 + fr; if (key > q) s[kb][qi][j] = -INFINITY; }
;                 }
;                 bf16x8 pf[2][2];
; #pragma unroll
;                 for (int qi = 0; qi < 2; ++qi) {
;                     float mx = -INFINITY;
; #pragma unroll
;                     for (int kb = 0; kb < 4; ++kb) mx = fmaxf(mx, fmaxf(fmaxf(s[kb][qi][0], s[kb][qi][1]), fmaxf(s[kb][qi][2], s[kb][qi][3])));
;                     mx = fmaxf(mx, __shfl_xor(mx, 16)); mx = fmaxf(mx, __shfl_xor(mx, 32));
	v_or_b32_e32 v69, s31, v242
	v_cmp_gt_i32_e32 vcc, v69, v244
	v_mov_b32_e32 v68, s78
	v_cmp_lt_i32_e64 s[4:5], v69, v244
	v_cndmask_b32_e32 v68, v72, v68, vcc
	v_or_b32_e32 v70, 2, v69
	v_cndmask_b32_e64 v72, v68, v72, s[4:5]
	v_cndmask_b32_e64 v73, v234, v73, s[4:5]
	v_cmp_le_i32_e64 s[4:5], v70, v244
	v_or_b32_e32 v71, 3, v69
	v_mov_b32_e32 v68, s78
	v_cndmask_b32_e64 v74, v234, v74, s[4:5]
	v_cmp_le_i32_e64 s[4:5], v71, v244
	v_or_b32_e32 v88, 19, v69
	v_or_b32_e32 v89, 35, v69
	v_cndmask_b32_e64 v75, v234, v75, s[4:5]
	v_cmp_gt_i32_e64 s[4:5], v69, v199
	s_nop 1
	v_cndmask_b32_e64 v68, v108, v68, s[4:5]
	v_cmp_lt_i32_e64 s[4:5], v69, v199
	s_nop 1
	v_cndmask_b32_e64 v108, v68, v108, s[4:5]
	v_cndmask_b32_e64 v109, v234, v109, s[4:5]
	v_cmp_le_i32_e64 s[4:5], v70, v199
	v_or_b32_e32 v68, 16, v69
	v_or_b32_e32 v70, 17, v69
	v_cndmask_b32_e64 v110, v234, v110, s[4:5]
	v_cmp_le_i32_e64 s[4:5], v71, v199
	v_or_b32_e32 v71, 18, v69
	s_nop 0
	v_cndmask_b32_e64 v111, v234, v111, s[4:5]
	v_cmp_gt_i32_e64 s[4:5], v68, v244
	v_mov_b32_e32 v68, s78
	v_cndmask_b32_e32 v76, v76, v68, vcc
	v_cmp_le_i32_e32 vcc, v70, v199
	v_cndmask_b32_e64 v80, v80, v68, s[4:5]
	v_cmp_le_i32_e64 s[4:5], v70, v244
	v_cndmask_b32_e32 v77, v234, v77, vcc
	v_cmp_le_i32_e32 vcc, v71, v199
	v_or_b32_e32 v70, 32, v69
	v_cndmask_b32_e64 v81, v234, v81, s[4:5]
	v_cndmask_b32_e32 v78, v234, v78, vcc
	v_cmp_le_i32_e32 vcc, v88, v199
	v_cmp_le_i32_e64 s[4:5], v71, v244
	v_or_b32_e32 v71, 33, v69
	v_cndmask_b32_e32 v79, v234, v79, vcc
	v_cmp_gt_i32_e32 vcc, v70, v244
	v_cndmask_b32_e64 v82, v234, v82, s[4:5]
	v_cmp_le_i32_e64 s[4:5], v88, v244
	v_cndmask_b32_e32 v84, v84, v68, vcc
	v_cmp_le_i32_e32 vcc, v71, v244
	v_or_b32_e32 v88, 34, v69
	v_cndmask_b32_e64 v83, v234, v83, s[4:5]
	v_cndmask_b32_e32 v85, v234, v85, vcc
	v_cmp_le_i32_e32 vcc, v88, v244
	s_nop 1
	v_cndmask_b32_e32 v86, v234, v86, vcc
	v_cmp_le_i32_e32 vcc, v89, v244
	s_nop 1
	v_cndmask_b32_e32 v87, v234, v87, vcc
	v_cmp_gt_i32_e32 vcc, v70, v199
	v_or_b32_e32 v70, 48, v69
	s_nop 0
	v_cndmask_b32_e32 v104, v104, v68, vcc
	v_cmp_le_i32_e32 vcc, v71, v199
	v_or_b32_e32 v71, 49, v69
	s_nop 0
	v_cndmask_b32_e32 v105, v234, v105, vcc
	v_cmp_le_i32_e32 vcc, v88, v199
	v_or_b32_e32 v88, 50, v69
	v_or_b32_e32 v69, 51, v69
	v_cndmask_b32_e32 v106, v234, v106, vcc
	v_cmp_le_i32_e32 vcc, v89, v199
	s_nop 1
	v_cndmask_b32_e32 v107, v234, v107, vcc
	v_cmp_gt_i32_e32 vcc, v70, v244
	s_nop 1
	v_cndmask_b32_e32 v64, v64, v68, vcc
	v_cmp_le_i32_e32 vcc, v71, v244
	s_nop 1
	v_cndmask_b32_e32 v65, v234, v65, vcc
	v_cmp_le_i32_e32 vcc, v88, v244
	s_nop 1
	v_cndmask_b32_e32 v66, v234, v66, vcc
	v_cmp_le_i32_e32 vcc, v69, v244
	s_nop 1
	v_cndmask_b32_e32 v67, v234, v67, vcc
	v_cmp_gt_i32_e32 vcc, v70, v199
	s_nop 1
	v_cndmask_b32_e32 v116, v116, v68, vcc
	v_cmp_le_i32_e32 vcc, v71, v199
	s_nop 1
	v_cndmask_b32_e32 v117, v234, v117, vcc
	v_cmp_le_i32_e32 vcc, v88, v199
	s_nop 1
	v_cndmask_b32_e32 v118, v234, v118, vcc
	v_cmp_le_i32_e32 vcc, v69, v199
	s_nop 1
	v_cndmask_b32_e32 v119, v234, v119, vcc
.LBB0_152:
	s_waitcnt lgkmcnt(0)
	s_barrier
	v_mbcnt_hi_u32_b32 v208, -1, v235
	v_and_b32_e32 v68, 64, v208
	v_xor_b32_e32 v211, 16, v208
	v_add_u32_e32 v209, 64, v68
	v_cmp_lt_i32_e32 vcc, v211, v209
	v_xor_b32_e32 v210, 32, v208
	v_max_f32_e32 v69, v74, v74
	v_cndmask_b32_e32 v68, v208, v211, vcc
	v_cmp_lt_i32_e32 vcc, v210, v209
	v_lshlrev_b32_e32 v121, 2, v68
	v_max_f32_e32 v70, v82, v82
	v_cndmask_b32_e32 v68, v208, v210, vcc
	v_lshlrev_b32_e32 v122, 2, v68
	v_max_f32_e32 v68, v75, v75
	v_max_f32_e32 v68, v69, v68
	v_max_f32_e32 v69, v83, v83
	v_max_f32_e32 v69, v70, v69
	v_max3_f32 v68, v72, v73, v68
	v_max3_f32 v69, v80, v81, v69
	v_max3_f32 v68, v68, s78, v69
	v_max_f32_e32 v69, v87, v87
	v_max_f32_e32 v70, v86, v86
	v_max_f32_e32 v69, v70, v69
	v_max_f32_e32 v70, v67, v67
	v_max_f32_e32 v71, v66, v66
	v_max_f32_e32 v70, v71, v70
	v_max3_f32 v69, v84, v85, v69
	v_max3_f32 v70, v64, v65, v70
	v_max3_f32 v68, v68, v69, v70
	ds_bpermute_b32 v69, v121, v68
	v_max_f32_e32 v123, v111, v111
	v_max_f32_e32 v124, v110, v110
	v_max_f32_e32 v123, v124, v123
	v_max_f32_e32 v124, v79, v79
	s_waitcnt lgkmcnt(0)
	v_max_f32_e32 v69, v69, v69
	v_max_f32_e32 v68, v68, v69
	ds_bpermute_b32 v69, v122, v68
	v_max_f32_e32 v125, v78, v78
	v_max_f32_e32 v124, v125, v124
	v_max3_f32 v123, v108, v109, v123
	v_max3_f32 v124, v76, v77, v124
	s_waitcnt lgkmcnt(0)
; #define LAS __attribute__((address_space(3)))
; __device__ __forceinline__ void attn_phase(LAS unsigned char* lds, const bf16_t* Q, const bf16_t* KN, const bf16_t* P, const bf16_t* VT, bf16_t* CAT, int bid, int G, const int tid) {
;     ...
;                 for (int qi = 0; qi < 2; ++qi) {
;                     float mx = -INFINITY;
; #pragma unroll
;                     for (int kb = 0; kb < 4; ++kb) mx = fmaxf(mx, fmaxf(fmaxf(s[kb][qi][0], s[kb][qi][1]), fmaxf(s[kb][qi][2], s[kb][qi][3])));
;                     mx = fmaxf(mx, __shfl_xor(mx, 16)); mx = fmaxf(mx, __shfl_xor(mx, 32));
;                     const float mnew = fmaxf(mrow[qi], mx);
;                     const float alpha = __builtin_amdgcn_exp2f(mrow[qi] - mnew);
;                     mrow[qi] = mnew;
;                     float ps = 0.f;
; #pragma unroll
;                     for (int kb = 0; kb < 4; ++kb)
; #pragma unroll
;                         for (int j = 0; j < 4; ++j) { const float e = __builtin_amdgcn_exp2f(s[kb][qi][j] - mnew); s[kb][qi][j] = e; ps += e; }
;                     lrow[qi] = lrow[qi] * alpha + ps;
; #pragma unroll
;                     for (int d = 0; d < 8; ++d) o[d][qi] = o[d][qi] * alpha;
; #pragma unroll
;                     for (int cc = 0; cc < 2; ++cc) {
;                         u32x4 t; t.x = cvt_pk_bf16(s[2 * cc][qi][0], s[2 * cc][qi][1]); t.y = cvt_pk_bf16(s[2 * cc][qi][2], s[2 * cc][qi][3]);
;                         t.z = cvt_pk_bf16(s[2 * cc + 1][qi][0], s[2 * cc + 1][qi][1]); t.w = cvt_pk_bf16(s[2 * cc + 1][qi][2], s[2 * cc + 1][qi][3]);
;                         pf[qi][cc] = __builtin_bit_cast(bf16x8, t);
;                     }
;                 }
; #pragma unroll
;                 for (int cc = 0; cc < 2; ++cc)
; #pragma unroll
;                     for (int d = 0; d < 8; ++d) {
;                         const LAS unsigned char* vp = buf + KBYTES + ((d * 16 + fr) * VS + 32 * cc + 4 * fq) * 2;
;                         const u32x2 v0 = *(const LAS u32x2*)vp, v1 = *(const LAS u32x2*)(vp + 32);
;                         const u32x4 vv = {v0.x, v0.y, v1.x, v1.y};
;                         const bf16x8 vf = __builtin_bit_cast(bf16x8, vv);
;                         o[d][0] = __builtin_amdgcn_mfma_f32_16x16x32_bf16(vf, pf[0][cc], o[d][0], 0, 0, 0);
;                         o[d][1] = __builtin_amdgcn_mfma_f32_16x16x32_bf16(vf, pf[1][cc], o[d][1], 0, 0, 0);
	v_max3_f32 v68, v207, v68, v69
	v_sub_f32_e32 v70, v72, v68
	v_exp_f32_e32 v129, v70
	v_sub_f32_e32 v70, v73, v68
	v_exp_f32_e32 v131, v70
	v_sub_f32_e32 v70, v74, v68
	v_exp_f32_e32 v145, v70
	v_sub_f32_e32 v70, v75, v68
	v_exp_f32_e32 v147, v70
	v_sub_f32_e32 v70, v80, v68
	v_exp_f32_e32 v149, v70
	v_sub_f32_e32 v70, v81, v68
	v_exp_f32_e32 v151, v70
	v_sub_f32_e32 v70, v82, v68
	v_sub_f32_e32 v69, v207, v68
	v_exp_f32_e32 v153, v70
	v_sub_f32_e32 v70, v83, v68
	v_max3_f32 v123, v123, s78, v124
	v_max_f32_e32 v124, v107, v107
	v_max_f32_e32 v125, v106, v106
	v_exp_f32_e32 v155, v70
	v_sub_f32_e32 v70, v84, v68
	v_exp_f32_e32 v120, v69
	v_max_f32_e32 v124, v125, v124
	v_max_f32_e32 v125, v119, v119
	v_max_f32_e32 v126, v118, v118
	v_exp_f32_e32 v157, v70
	v_sub_f32_e32 v70, v85, v68
	v_sub_f32_e32 v64, v64, v68
	v_max_f32_e32 v125, v126, v125
	v_exp_f32_e32 v159, v70
	v_sub_f32_e32 v70, v86, v68
	v_exp_f32_e32 v165, v64
	v_sub_f32_e32 v64, v65, v68
	v_max3_f32 v124, v104, v105, v124
	v_max3_f32 v125, v116, v117, v125
	v_exp_f32_e32 v161, v70
	v_sub_f32_e32 v70, v87, v68
	v_exp_f32_e32 v167, v64
	v_sub_f32_e32 v64, v66, v68
	v_max3_f32 v123, v123, v124, v125
	v_exp_f32_e32 v163, v70
	v_exp_f32_e32 v169, v64
	v_sub_f32_e32 v64, v67, v68
	v_pk_mul_f32 v[114:115], v[34:35], v[120:121] op_sel_hi:[1,0]
	v_pk_mul_f32 v[112:113], v[32:33], v[120:121] op_sel_hi:[1,0]
	v_pk_mul_f32 v[102:103], v[38:39], v[120:121] op_sel_hi:[1,0]
	v_pk_mul_f32 v[100:101], v[36:37], v[120:121] op_sel_hi:[1,0]
	v_pk_mul_f32 v[98:99], v[42:43], v[120:121] op_sel_hi:[1,0]
	v_pk_mul_f32 v[96:97], v[40:41], v[120:121] op_sel_hi:[1,0]
	v_pk_mul_f32 v[94:95], v[46:47], v[120:121] op_sel_hi:[1,0]
	v_pk_mul_f32 v[92:93], v[44:45], v[120:121] op_sel_hi:[1,0]
	v_pk_mul_f32 v[90:91], v[54:55], v[120:121] op_sel_hi:[1,0]
	v_pk_mul_f32 v[88:89], v[52:53], v[120:121] op_sel_hi:[1,0]
	v_pk_mul_f32 v[86:87], v[50:51], v[120:121] op_sel_hi:[1,0]
	v_pk_mul_f32 v[84:85], v[48:49], v[120:121] op_sel_hi:[1,0]
	v_pk_mul_f32 v[82:83], v[58:59], v[120:121] op_sel_hi:[1,0]
	v_pk_mul_f32 v[80:81], v[56:57], v[120:121] op_sel_hi:[1,0]
	v_pk_mul_f32 v[70:71], v[62:63], v[120:121] op_sel_hi:[1,0]
	v_pk_mul_f32 v[68:69], v[60:61], v[120:121] op_sel_hi:[1,0]
	ds_bpermute_b32 v121, v121, v123
	v_cvt_pk_bf16_f32 v75, v153, v155
	v_cvt_pk_bf16_f32 v73, v145, v147
	v_cvt_pk_bf16_f32 v72, v129, v131
	v_cvt_pk_bf16_f32 v74, v149, v151
	s_waitcnt lgkmcnt(0)
	v_max_f32_e32 v121, v121, v121
	v_max_f32_e32 v121, v123, v121
	ds_bpermute_b32 v122, v122, v121
	v_exp_f32_e32 v171, v64
	v_cvt_pk_bf16_f32 v64, v157, v159
	v_cvt_pk_bf16_f32 v65, v161, v163
	v_cvt_pk_bf16_f32 v66, v165, v167
	s_waitcnt lgkmcnt(0)
	v_max3_f32 v121, v206, v121, v122
	v_sub_f32_e32 v108, v108, v121
	v_exp_f32_e32 v128, v108
	v_sub_f32_e32 v108, v109, v121
	v_exp_f32_e32 v130, v108
	v_sub_f32_e32 v108, v110, v121
	v_exp_f32_e32 v144, v108
	v_sub_f32_e32 v108, v111, v121
	v_sub_f32_e32 v76, v76, v121
	v_exp_f32_e32 v146, v108
	v_exp_f32_e32 v148, v76
	v_sub_f32_e32 v76, v77, v121
	v_exp_f32_e32 v150, v76
	v_pk_add_f32 v[76:77], v[128:129], 0 op_sel_hi:[1,0]
	v_sub_f32_e32 v78, v78, v121
	v_pk_add_f32 v[76:77], v[130:131], v[76:77]
	v_exp_f32_e32 v152, v78
	v_pk_add_f32 v[76:77], v[144:145], v[76:77]
	v_sub_f32_e32 v78, v79, v121
	v_pk_add_f32 v[76:77], v[146:147], v[76:77]
	v_exp_f32_e32 v154, v78
	v_pk_add_f32 v[76:77], v[148:149], v[76:77]
	v_sub_f32_e32 v78, v104, v121
	v_pk_add_f32 v[76:77], v[150:151], v[76:77]
	v_exp_f32_e32 v156, v78
	v_sub_f32_e32 v78, v105, v121
	v_exp_f32_e32 v158, v78
	v_sub_f32_e32 v78, v106, v121
	v_pk_add_f32 v[76:77], v[152:153], v[76:77]
	v_cvt_pk_bf16_f32 v111, v152, v154
	v_add3_u32 v152, s30, v180, v243
	v_exp_f32_e32 v160, v78
	v_sub_f32_e32 v78, v107, v121
	v_add_u32_e32 v153, 0x6000, v152
	v_exp_f32_e32 v162, v78
	v_sub_f32_e32 v78, v116, v121
	v_cvt_pk_bf16_f32 v109, v144, v146
	ds_read2_b64 v[144:147], v153 offset0:128 offset1:132
	v_exp_f32_e32 v164, v78
	v_sub_f32_e32 v78, v117, v121
	v_exp_f32_e32 v166, v78
	v_sub_f32_e32 v78, v118, v121
	v_sub_f32_e32 v122, v206, v121
	v_exp_f32_e32 v168, v78
	v_sub_f32_e32 v78, v119, v121
	v_exp_f32_e32 v170, v78
	v_exp_f32_e32 v78, v122
	v_mov_b32_e32 v79, v120
	v_pk_add_f32 v[76:77], v[154:155], v[76:77]
	v_add_u32_e32 v154, 0x6800, v152
	v_pk_mul_f32 v[174:175], v[2:3], v[78:79] op_sel_hi:[1,0]
	v_pk_mul_f32 v[172:173], v[0:1], v[78:79] op_sel_hi:[1,0]
	v_cvt_pk_bf16_f32 v108, v128, v130
	v_cvt_pk_bf16_f32 v110, v148, v150
	s_waitcnt lgkmcnt(0)
	v_mfma_f32_16x16x32_bf16 v[128:131], v[144:147], v[72:75], v[112:115]
	v_mul_f32_e64 v142, v6, v78
	v_mul_f32_e64 v143, v7, v78
	v_pk_mul_f32 v[140:141], v[4:5], v[78:79] op_sel_hi:[1,0]
	v_add_u32_e32 v155, 0x7000, v152
	v_mfma_f32_16x16x32_bf16 v[112:115], v[144:147], v[108:111], v[172:175]
	ds_read2_b64 v[144:147], v154 offset0:160 offset1:164
	v_pk_add_f32 v[76:77], v[156:157], v[76:77]
	v_pk_mul_f32 v[138:139], v[10:11], v[78:79] op_sel_hi:[1,0]
	s_waitcnt lgkmcnt(0)
; #define LAS __attribute__((address_space(3)))
; __device__ __forceinline__ void attn_phase(LAS unsigned char* lds, const bf16_t* Q, const bf16_t* KN, const bf16_t* P, const bf16_t* VT, bf16_t* CAT, int bid, int G, const int tid) {
;     ...
; #pragma unroll
;                 for (int cc = 0; cc < 2; ++cc)
; #pragma unroll
;                     for (int d = 0; d < 8; ++d) {
;                         const LAS unsigned char* vp = buf + KBYTES + ((d * 16 + fr) * VS + 32 * cc + 4 * fq) * 2;
;                         const u32x2 v0 = *(const LAS u32x2*)vp, v1 = *(const LAS u32x2*)(vp + 32);
;                         const u32x4 vv = {v0.x, v0.y, v1.x, v1.y};
;                         const bf16x8 vf = __builtin_bit_cast(bf16x8, vv);
;                         o[d][0] = __builtin_amdgcn_mfma_f32_16x16x32_bf16(vf, pf[0][cc], o[d][0], 0, 0, 0);
;                         o[d][1] = __builtin_amdgcn_mfma_f32_16x16x32_bf16(vf, pf[1][cc], o[d][1], 0, 0, 0);
;                     }
;             }
;         }
	v_mfma_f32_16x16x32_bf16 v[100:103], v[144:147], v[72:75], v[100:103]
	v_add_f32_e64 v76, v158, v76
	v_add_f32_e64 v77, v159, v77
	v_pk_mul_f32 v[136:137], v[8:9], v[78:79] op_sel_hi:[1,0]
	v_pk_add_f32 v[76:77], v[160:161], v[76:77]
	v_mfma_f32_16x16x32_bf16 v[140:143], v[144:147], v[108:111], v[140:143]
	ds_read2_b64 v[144:147], v155 offset0:192 offset1:196
	v_pk_add_f32 v[76:77], v[162:163], v[76:77]
	v_pk_mul_f32 v[134:135], v[14:15], v[78:79] op_sel_hi:[1,0]
	v_pk_add_f32 v[76:77], v[164:165], v[76:77]
	s_waitcnt lgkmcnt(0)
	v_mfma_f32_16x16x32_bf16 v[96:99], v[144:147], v[72:75], v[96:99]
	v_add_f32_e64 v76, v166, v76
	v_add_f32_e64 v77, v167, v77
	v_pk_mul_f32 v[132:133], v[12:13], v[78:79] op_sel_hi:[1,0]
	v_pk_add_f32 v[76:77], v[168:169], v[76:77]
	v_mfma_f32_16x16x32_bf16 v[144:147], v[144:147], v[108:111], v[136:139]
	v_add_f32_e64 v76, v170, v76
	v_add_f32_e64 v77, v171, v77
	v_add_u32_e32 v199, 0x8800, v152
	v_pk_fma_f32 v[204:205], v[202:203], v[78:79], v[76:77]
	v_cvt_pk_bf16_f32 v76, v156, v158
	v_add_u32_e32 v156, 0x7800, v152
	ds_read2_b64 v[136:139], v156 offset0:224 offset1:228
	s_waitcnt lgkmcnt(0)
	v_mfma_f32_16x16x32_bf16 v[92:95], v[136:139], v[72:75], v[92:95]
	v_mul_f32_e64 v126, v18, v78
	v_mul_f32_e64 v127, v19, v78
	v_pk_mul_f32 v[124:125], v[16:17], v[78:79] op_sel_hi:[1,0]
	v_add_u32_e32 v206, 0x9000, v152
	v_mfma_f32_16x16x32_bf16 v[132:135], v[136:139], v[108:111], v[132:135]
	ds_read2_b64 v[136:139], v199 offset1:4
	v_pk_mul_f32 v[122:123], v[22:23], v[78:79] op_sel_hi:[1,0]
	v_pk_mul_f32 v[120:121], v[20:21], v[78:79] op_sel_hi:[1,0]
	s_waitcnt lgkmcnt(0)
	v_mfma_f32_16x16x32_bf16 v[148:151], v[136:139], v[108:111], v[124:127]
	s_nop 2
	ds_read2_b64 v[124:127], v206 offset0:32 offset1:36
	v_add_u32_e32 v207, 0x9800, v152
	v_pk_mul_f32 v[118:119], v[26:27], v[78:79] op_sel_hi:[1,0]
	s_waitcnt lgkmcnt(0)
	v_mfma_f32_16x16x32_bf16 v[172:175], v[124:127], v[108:111], v[120:123]
	s_nop 2
	ds_read2_b64 v[120:123], v207 offset0:64 offset1:68
	v_pk_mul_f32 v[116:117], v[24:25], v[78:79] op_sel_hi:[1,0]
	v_add_u32_e32 v216, 0xa000, v152
	v_pk_mul_f32 v[106:107], v[30:31], v[78:79] op_sel_hi:[1,0]
	s_waitcnt lgkmcnt(0)
	v_mfma_f32_16x16x32_bf16 v[212:215], v[120:123], v[108:111], v[116:119]
	s_nop 2
	ds_read2_b64 v[116:119], v216 offset0:96 offset1:100
	v_pk_mul_f32 v[104:105], v[28:29], v[78:79] op_sel_hi:[1,0]
	v_cvt_pk_bf16_f32 v67, v169, v171
	v_mfma_f32_16x16x32_bf16 v[88:91], v[136:139], v[72:75], v[88:91]
	v_cvt_pk_bf16_f32 v77, v160, v162
	v_cvt_pk_bf16_f32 v78, v164, v166
	v_cvt_pk_bf16_f32 v79, v168, v170
	v_mfma_f32_16x16x32_bf16 v[84:87], v[124:127], v[72:75], v[84:87]
	s_mov_b64 s[4:5], 0
	v_mfma_f32_16x16x32_bf16 v[80:83], v[120:123], v[72:75], v[80:83]
	s_waitcnt lgkmcnt(0)
	v_mfma_f32_16x16x32_bf16 v[72:75], v[116:119], v[72:75], v[68:71]
	v_mfma_f32_16x16x32_bf16 v[68:71], v[116:119], v[108:111], v[104:107]
	s_nop 2
	ds_read2_b64 v[104:107], v153 offset0:136 offset1:140
	s_waitcnt lgkmcnt(0)
	v_mfma_f32_16x16x32_bf16 v[160:163], v[104:107], v[64:67], v[128:131]
	v_mfma_f32_16x16x32_bf16 v[136:139], v[104:107], v[76:79], v[112:115]
	ds_read2_b64 v[104:107], v154 offset0:168 offset1:172
	s_waitcnt lgkmcnt(0)
	v_mfma_f32_16x16x32_bf16 v[168:171], v[104:107], v[64:67], v[100:103]
	s_nop 2
	ds_read2_b64 v[100:103], v155 offset0:200 offset1:204
	s_waitcnt lgkmcnt(0)
	v_mfma_f32_16x16x32_bf16 v[164:167], v[100:103], v[64:67], v[96:99]
	s_nop 2
	ds_read2_b64 v[96:99], v156 offset0:232 offset1:236
	s_waitcnt lgkmcnt(0)
	v_mfma_f32_16x16x32_bf16 v[156:159], v[96:99], v[64:67], v[92:95]
	s_nop 2
	ds_read2_b64 v[92:95], v199 offset0:8 offset1:12
	s_waitcnt lgkmcnt(0)
	v_mfma_f32_16x16x32_bf16 v[152:155], v[92:95], v[64:67], v[88:91]
	s_nop 2
	ds_read2_b64 v[88:91], v206 offset0:40 offset1:44
	v_mfma_f32_16x16x32_bf16 v[116:119], v[92:95], v[76:79], v[148:151]
	s_waitcnt lgkmcnt(0)
	v_mfma_f32_16x16x32_bf16 v[148:151], v[88:91], v[64:67], v[84:87]
	s_nop 2
	ds_read2_b64 v[84:87], v207 offset0:72 offset1:76
	v_mfma_f32_16x16x32_bf16 v[124:127], v[100:103], v[76:79], v[144:147]
	s_waitcnt lgkmcnt(0)
	v_mfma_f32_16x16x32_bf16 v[144:147], v[84:87], v[64:67], v[80:83]
	s_nop 2
	ds_read2_b64 v[80:83], v216 offset0:104 offset1:108
	v_mfma_f32_16x16x32_bf16 v[128:131], v[104:107], v[76:79], v[140:143]
	v_mfma_f32_16x16x32_bf16 v[120:123], v[96:99], v[76:79], v[132:135]
	v_mfma_f32_16x16x32_bf16 v[112:115], v[88:91], v[76:79], v[172:175]
	v_mfma_f32_16x16x32_bf16 v[132:135], v[84:87], v[76:79], v[212:215]
	s_waitcnt lgkmcnt(0)
	v_mfma_f32_16x16x32_bf16 v[172:175], v[80:83], v[64:67], v[72:75]
	v_mfma_f32_16x16x32_bf16 v[140:143], v[80:83], v[76:79], v[68:71]
.LBB0_153:
	s_cmp_lg_u32 s80, 0
	s_cbranch_scc1 .Lat_last_done
	s_barrier

; #define LAS __attribute__((address_space(3)))
; __device__ __forceinline__ void attn_phase(LAS unsigned char* lds, const bf16_t* Q, const bf16_t* KN, const bf16_t* P, const bf16_t* VT, bf16_t* CAT, int bid, int G, const int tid) {
;     ...
;         for (int kt = 0; kt < nt; ++kt) {
;             LAS unsigned char* buf = lds + (kt & 1) * BUFB;
;             *(LAS u32x4*)(buf + lk) = rk0; *(LAS u32x4*)(buf + lk + 32 * KS * 2) = rk1; *(LAS u32x4*)(buf + lp) = rp;
;             *(LAS u32x4*)(buf + lv) = rv0; *(LAS u32x4*)(buf + lv + 64 * VS * 2) = rv1;
;             __syncthreads();
;             if (kt + 1 < nt) {
;                 const size_t ko = (size_t)(kt + 1) * 64;
;                 rk0 = *(const u32x4*)(gk + ko * 1024); rk1 = *(const u32x4*)(gk + (ko + 32) * 1024); rp = *(const u32x4*)(gp + ko * P_LD);
;                 rv0 = *(const u32x4*)(gv + ko); rv1 = *(const u32x4*)(gv + (size_t)64 * M + ko);
;             }
;             if (kt * 64 <= qlo + 31) {
.Lat_last_skip:
	s_barrier
	s_branch .LBB0_153
